# adds: 256-byte alignment of the four GEMM K-loop heads
# speedup vs baseline: 1.0043x; 1.0043x over previous
.LBB0_125:
	s_ashr_i32 s77, s76, 31
	s_lshl_b64 s[18:19], s[76:77], 21
	s_add_u32 s58, s86, s18
	s_addc_u32 s59, s87, s19
	s_and_b64 s[18:19], s[6:7], exec
	s_cselect_b32 s11, s59, s9
	s_cselect_b32 s13, s58, s8
	s_ashr_i32 s17, s16, 31
	s_lshl_b64 s[18:19], s[16:17], 21
	s_add_u32 s36, s96, s18
	s_addc_u32 s37, s97, s19
	s_and_b64 s[18:19], s[6:7], exec
	s_cselect_b32 s17, s37, s15
	s_cselect_b32 s20, s36, s14
	s_add_u32 s8, s8, 0x100080
	s_addc_u32 s9, s9, 0
	s_add_u32 s21, s14, 0x100
	s_addc_u32 s28, s15, 0
	s_mov_b32 s29, -2
	ds_read_b128 v[130:133], v176
	ds_read_b128 v[134:137], v176 offset:1024
	ds_read_b128 v[170:173], v176 offset:2048
	ds_read_b128 v[180:183], v176 offset:3072
	ds_read_b128 v[184:187], v177
	ds_read_b128 v[188:191], v177 offset:1024
	ds_read_b128 v[192:195], v177 offset:2048
	ds_read_b128 v[198:201], v177 offset:3072
	s_add_u32 s14, s8, 0xfff00080
	s_addc_u32 s15, s9, -1
	s_cmp_eq_u32 s29, 60
	s_cselect_b32 s19, s11, s15
	s_cselect_b32 s18, s13, s14
	s_cselect_b32 s15, s17, s28
	s_cselect_b32 s14, s20, s21
	s_add_i32 m0, s73, 0xc000
	ds_read_b128 v[202:205], v178
	ds_read_b128 v[206:209], v178 offset:1024
	ds_read_b128 v[210:213], v178 offset:2048
	ds_read_b128 v[214:217], v178 offset:3072
	ds_read_b128 v[218:221], v178 offset:4096
	ds_read_b128 v[222:225], v178 offset:5120
	ds_read_b128 v[226:229], v178 offset:6144
	ds_read_b128 v[230:233], v178 offset:7168
	global_load_lds_dwordx4 v160, s[8:9]
	s_add_i32 m0, s73, 0xe000
	s_nop 0
	global_load_lds_dwordx4 v162, s[8:9]
	s_waitcnt vmcnt(8)
	s_waitcnt lgkmcnt(0)
	s_setprio 1
	s_barrier
	v_mfma_f32_16x16x32_bf16 v[126:129], v[130:133], v[202:205], 0
	v_mfma_f32_16x16x32_bf16 v[122:125], v[170:173], v[202:205], 0
	v_mfma_f32_16x16x32_bf16 v[110:113], v[130:133], v[210:213], 0
	v_mfma_f32_16x16x32_bf16 v[106:109], v[170:173], v[210:213], 0
	v_mfma_f32_16x16x32_bf16 v[94:97], v[130:133], v[218:221], 0
	v_mfma_f32_16x16x32_bf16 v[90:93], v[170:173], v[218:221], 0
	v_mfma_f32_16x16x32_bf16 v[78:81], v[130:133], v[226:229], 0
	v_mfma_f32_16x16x32_bf16 v[74:77], v[170:173], v[226:229], 0
	v_mfma_f32_16x16x32_bf16 v[126:129], v[134:137], v[206:209], v[126:129]
	v_mfma_f32_16x16x32_bf16 v[122:125], v[180:183], v[206:209], v[122:125]
	v_mfma_f32_16x16x32_bf16 v[110:113], v[134:137], v[214:217], v[110:113]
	v_mfma_f32_16x16x32_bf16 v[106:109], v[180:183], v[214:217], v[106:109]
	v_mfma_f32_16x16x32_bf16 v[94:97], v[134:137], v[222:225], v[94:97]
	v_mfma_f32_16x16x32_bf16 v[90:93], v[180:183], v[222:225], v[90:93]
	v_mfma_f32_16x16x32_bf16 v[78:81], v[134:137], v[230:233], v[78:81]
	v_mfma_f32_16x16x32_bf16 v[74:77], v[180:183], v[230:233], v[74:77]
	v_mfma_f32_16x16x32_bf16 v[118:121], v[184:187], v[202:205], 0
	v_mfma_f32_16x16x32_bf16 v[114:117], v[192:195], v[202:205], 0
	v_mfma_f32_16x16x32_bf16 v[102:105], v[184:187], v[210:213], 0
	v_mfma_f32_16x16x32_bf16 v[98:101], v[192:195], v[210:213], 0
	v_mfma_f32_16x16x32_bf16 v[86:89], v[184:187], v[218:221], 0
	v_mfma_f32_16x16x32_bf16 v[82:85], v[192:195], v[218:221], 0
	v_mfma_f32_16x16x32_bf16 v[70:73], v[184:187], v[226:229], 0
	v_mfma_f32_16x16x32_bf16 v[66:69], v[192:195], v[226:229], 0
	v_mfma_f32_16x16x32_bf16 v[118:121], v[188:191], v[206:209], v[118:121]
	v_mfma_f32_16x16x32_bf16 v[114:117], v[198:201], v[206:209], v[114:117]
	v_mfma_f32_16x16x32_bf16 v[102:105], v[188:191], v[214:217], v[102:105]
	v_mfma_f32_16x16x32_bf16 v[98:101], v[198:201], v[214:217], v[98:101]
	v_mfma_f32_16x16x32_bf16 v[86:89], v[188:191], v[222:225], v[86:89]
	v_mfma_f32_16x16x32_bf16 v[82:85], v[198:201], v[222:225], v[82:85]
	v_mfma_f32_16x16x32_bf16 v[70:73], v[188:191], v[230:233], v[70:73]
	v_mfma_f32_16x16x32_bf16 v[66:69], v[198:201], v[230:233], v[66:69]
	s_barrier
	s_setprio 0
	s_add_i32 s30, s69, s35
	s_mov_b32 m0, s30
	ds_read_b128 v[202:205], v178 offset:16384
	ds_read_b128 v[206:209], v178 offset:17408
	ds_read_b128 v[210:213], v178 offset:18432
	ds_read_b128 v[214:217], v178 offset:19456
	ds_read_b128 v[218:221], v178 offset:20480
	ds_read_b128 v[222:225], v178 offset:21504
	ds_read_b128 v[226:229], v178 offset:22528
	ds_read_b128 v[230:233], v178 offset:23552
	global_load_lds_dwordx4 v140, s[14:15]
	s_add_i32 m0, s30, 0x2000
	s_add_u32 s30, s14, 0x100000
	s_addc_u32 s31, s15, 0
	s_add_i32 s38, s70, s35
	global_load_lds_dwordx4 v144, s[14:15]
	s_mov_b32 m0, s38
	global_load_lds_dwordx4 v140, s[30:31]
	s_add_i32 m0, s38, 0x2000
	s_nop 0
	global_load_lds_dwordx4 v144, s[30:31]
	s_mov_b32 m0, s73
	s_nop 0
	global_load_lds_dwordx4 v138, s[18:19]
	s_mov_b32 m0, s66
	s_nop 0
	global_load_lds_dwordx4 v142, s[18:19]
	s_waitcnt vmcnt(8)
	s_waitcnt lgkmcnt(0)
	s_setprio 1
	s_barrier
	v_mfma_f32_16x16x32_bf16 v[62:65], v[130:133], v[202:205], 0
	v_mfma_f32_16x16x32_bf16 v[58:61], v[170:173], v[202:205], 0
	v_mfma_f32_16x16x32_bf16 v[46:49], v[130:133], v[210:213], 0
	v_mfma_f32_16x16x32_bf16 v[42:45], v[170:173], v[210:213], 0
	v_mfma_f32_16x16x32_bf16 v[30:33], v[130:133], v[218:221], 0
	v_mfma_f32_16x16x32_bf16 v[26:29], v[170:173], v[218:221], 0
	v_mfma_f32_16x16x32_bf16 v[14:17], v[130:133], v[226:229], 0
	v_mfma_f32_16x16x32_bf16 v[10:13], v[170:173], v[226:229], 0
	v_mfma_f32_16x16x32_bf16 v[62:65], v[134:137], v[206:209], v[62:65]
	v_mfma_f32_16x16x32_bf16 v[58:61], v[180:183], v[206:209], v[58:61]
	v_mfma_f32_16x16x32_bf16 v[46:49], v[134:137], v[214:217], v[46:49]
	v_mfma_f32_16x16x32_bf16 v[42:45], v[180:183], v[214:217], v[42:45]
	v_mfma_f32_16x16x32_bf16 v[30:33], v[134:137], v[222:225], v[30:33]
	v_mfma_f32_16x16x32_bf16 v[26:29], v[180:183], v[222:225], v[26:29]
	v_mfma_f32_16x16x32_bf16 v[14:17], v[134:137], v[230:233], v[14:17]
	v_mfma_f32_16x16x32_bf16 v[10:13], v[180:183], v[230:233], v[10:13]
	v_mfma_f32_16x16x32_bf16 v[54:57], v[184:187], v[202:205], 0
	v_mfma_f32_16x16x32_bf16 v[50:53], v[192:195], v[202:205], 0
	v_mfma_f32_16x16x32_bf16 v[38:41], v[184:187], v[210:213], 0
	v_mfma_f32_16x16x32_bf16 v[34:37], v[192:195], v[210:213], 0
	v_mfma_f32_16x16x32_bf16 v[22:25], v[184:187], v[218:221], 0
	v_mfma_f32_16x16x32_bf16 v[18:21], v[192:195], v[218:221], 0
	v_mfma_f32_16x16x32_bf16 v[6:9], v[184:187], v[226:229], 0
	v_mfma_f32_16x16x32_bf16 v[2:5], v[192:195], v[226:229], 0
	v_mfma_f32_16x16x32_bf16 v[54:57], v[188:191], v[206:209], v[54:57]
	v_mfma_f32_16x16x32_bf16 v[50:53], v[198:201], v[206:209], v[50:53]
	v_mfma_f32_16x16x32_bf16 v[38:41], v[188:191], v[214:217], v[38:41]
	v_mfma_f32_16x16x32_bf16 v[34:37], v[198:201], v[214:217], v[34:37]
	v_mfma_f32_16x16x32_bf16 v[22:25], v[188:191], v[222:225], v[22:25]
	v_mfma_f32_16x16x32_bf16 v[18:21], v[198:201], v[222:225], v[18:21]
	v_mfma_f32_16x16x32_bf16 v[6:9], v[188:191], v[230:233], v[6:9]
	v_mfma_f32_16x16x32_bf16 v[2:5], v[198:201], v[230:233], v[2:5]
	s_barrier
	s_setprio 0
	s_add_i32 s30, 0, 0x18000
	v_add_u32_e32 v146, s30, v155
	s_add_i32 s31, 0, 0x1c000
	ds_read_b128 v[130:133], v146
	ds_read_b128 v[134:137], v146 offset:1024
	ds_read_b128 v[170:173], v146 offset:2048
	ds_read_b128 v[180:183], v146 offset:3072
	v_add_u32_e32 v146, s31, v155
	ds_read_b128 v[184:187], v146
	ds_read_b128 v[188:191], v146 offset:1024
	ds_read_b128 v[192:195], v146 offset:2048
	ds_read_b128 v[198:201], v146 offset:3072
	s_add_u32 s18, s18, 0x100000
	s_addc_u32 s19, s19, 0
	s_mov_b32 m0, s67
	ds_read_b128 v[202:205], v178 offset:32768
	ds_read_b128 v[206:209], v178 offset:33792
	ds_read_b128 v[210:213], v178 offset:34816
	ds_read_b128 v[214:217], v178 offset:35840
	ds_read_b128 v[218:221], v178 offset:36864
	ds_read_b128 v[222:225], v178 offset:37888
	ds_read_b128 v[226:229], v178 offset:38912
	ds_read_b128 v[230:233], v178 offset:39936
	global_load_lds_dwordx4 v138, s[18:19]
	s_mov_b32 m0, s88
	s_nop 0
	global_load_lds_dwordx4 v142, s[18:19]
	s_waitcnt vmcnt(8)
	s_waitcnt lgkmcnt(0)
	s_setprio 1
	s_barrier
	v_mfma_f32_16x16x32_bf16 v[126:129], v[130:133], v[202:205], v[126:129]
	v_mfma_f32_16x16x32_bf16 v[122:125], v[170:173], v[202:205], v[122:125]
	v_mfma_f32_16x16x32_bf16 v[110:113], v[130:133], v[210:213], v[110:113]
	v_mfma_f32_16x16x32_bf16 v[106:109], v[170:173], v[210:213], v[106:109]
	v_mfma_f32_16x16x32_bf16 v[94:97], v[130:133], v[218:221], v[94:97]
	v_mfma_f32_16x16x32_bf16 v[90:93], v[170:173], v[218:221], v[90:93]
	v_mfma_f32_16x16x32_bf16 v[78:81], v[130:133], v[226:229], v[78:81]
	v_mfma_f32_16x16x32_bf16 v[74:77], v[170:173], v[226:229], v[74:77]
	v_mfma_f32_16x16x32_bf16 v[126:129], v[134:137], v[206:209], v[126:129]
	v_mfma_f32_16x16x32_bf16 v[122:125], v[180:183], v[206:209], v[122:125]
	v_mfma_f32_16x16x32_bf16 v[110:113], v[134:137], v[214:217], v[110:113]
	v_mfma_f32_16x16x32_bf16 v[106:109], v[180:183], v[214:217], v[106:109]
	v_mfma_f32_16x16x32_bf16 v[94:97], v[134:137], v[222:225], v[94:97]
	v_mfma_f32_16x16x32_bf16 v[90:93], v[180:183], v[222:225], v[90:93]
	v_mfma_f32_16x16x32_bf16 v[78:81], v[134:137], v[230:233], v[78:81]
	v_mfma_f32_16x16x32_bf16 v[74:77], v[180:183], v[230:233], v[74:77]
	v_mfma_f32_16x16x32_bf16 v[118:121], v[184:187], v[202:205], v[118:121]
	v_mfma_f32_16x16x32_bf16 v[114:117], v[192:195], v[202:205], v[114:117]
	v_mfma_f32_16x16x32_bf16 v[102:105], v[184:187], v[210:213], v[102:105]
	v_mfma_f32_16x16x32_bf16 v[98:101], v[192:195], v[210:213], v[98:101]
	v_mfma_f32_16x16x32_bf16 v[86:89], v[184:187], v[218:221], v[86:89]
	v_mfma_f32_16x16x32_bf16 v[82:85], v[192:195], v[218:221], v[82:85]
	v_mfma_f32_16x16x32_bf16 v[70:73], v[184:187], v[226:229], v[70:73]
	v_mfma_f32_16x16x32_bf16 v[66:69], v[192:195], v[226:229], v[66:69]
	v_mfma_f32_16x16x32_bf16 v[118:121], v[188:191], v[206:209], v[118:121]
	v_mfma_f32_16x16x32_bf16 v[114:117], v[198:201], v[206:209], v[114:117]
	v_mfma_f32_16x16x32_bf16 v[102:105], v[188:191], v[214:217], v[102:105]
	v_mfma_f32_16x16x32_bf16 v[98:101], v[198:201], v[214:217], v[98:101]
	v_mfma_f32_16x16x32_bf16 v[86:89], v[188:191], v[222:225], v[86:89]
	v_mfma_f32_16x16x32_bf16 v[82:85], v[198:201], v[222:225], v[82:85]
	v_mfma_f32_16x16x32_bf16 v[70:73], v[188:191], v[230:233], v[70:73]
	v_mfma_f32_16x16x32_bf16 v[66:69], v[198:201], v[230:233], v[66:69]
	s_barrier
	s_setprio 0
	s_add_u32 s14, s14, 0x80
	s_addc_u32 s15, s15, 0
	s_add_i32 m0, s35, 0x18000
	ds_read_b128 v[202:205], v178 offset:49152
	ds_read_b128 v[206:209], v178 offset:50176
	ds_read_b128 v[210:213], v178 offset:51200
	ds_read_b128 v[214:217], v178 offset:52224
	ds_read_b128 v[218:221], v178 offset:53248
	ds_read_b128 v[222:225], v178 offset:54272
	ds_read_b128 v[226:229], v178 offset:55296
	ds_read_b128 v[230:233], v178 offset:56320
	global_load_lds_dwordx4 v140, s[14:15]
	s_add_i32 m0, s35, 0x1a000
	s_add_u32 s18, s18, 0xfff00080
	global_load_lds_dwordx4 v144, s[14:15]
	s_addc_u32 s19, s19, -1
	s_add_u32 s14, s14, 0x100000
	s_addc_u32 s15, s15, 0
	s_add_i32 m0, s35, 0x1c000
	s_nop 0
	global_load_lds_dwordx4 v140, s[14:15]
	s_add_i32 m0, s35, 0x1e000
	s_nop 0
	global_load_lds_dwordx4 v144, s[14:15]
	s_mov_b32 m0, s89
	s_nop 0
	global_load_lds_dwordx4 v138, s[18:19]
	s_mov_b32 m0, s68
	s_nop 0
	global_load_lds_dwordx4 v142, s[18:19]
	s_waitcnt vmcnt(8)
	s_waitcnt lgkmcnt(0)
	s_setprio 1
	s_barrier
	v_mfma_f32_16x16x32_bf16 v[62:65], v[130:133], v[202:205], v[62:65]
	v_mfma_f32_16x16x32_bf16 v[58:61], v[170:173], v[202:205], v[58:61]
	v_mfma_f32_16x16x32_bf16 v[46:49], v[130:133], v[210:213], v[46:49]
	v_mfma_f32_16x16x32_bf16 v[42:45], v[170:173], v[210:213], v[42:45]
	v_mfma_f32_16x16x32_bf16 v[30:33], v[130:133], v[218:221], v[30:33]
	v_mfma_f32_16x16x32_bf16 v[26:29], v[170:173], v[218:221], v[26:29]
	v_mfma_f32_16x16x32_bf16 v[14:17], v[130:133], v[226:229], v[14:17]
	v_mfma_f32_16x16x32_bf16 v[10:13], v[170:173], v[226:229], v[10:13]
	v_mfma_f32_16x16x32_bf16 v[62:65], v[134:137], v[206:209], v[62:65]
	v_mfma_f32_16x16x32_bf16 v[58:61], v[180:183], v[206:209], v[58:61]
	v_mfma_f32_16x16x32_bf16 v[46:49], v[134:137], v[214:217], v[46:49]
	v_mfma_f32_16x16x32_bf16 v[42:45], v[180:183], v[214:217], v[42:45]
	v_mfma_f32_16x16x32_bf16 v[30:33], v[134:137], v[222:225], v[30:33]
	v_mfma_f32_16x16x32_bf16 v[26:29], v[180:183], v[222:225], v[26:29]
	v_mfma_f32_16x16x32_bf16 v[14:17], v[134:137], v[230:233], v[14:17]
	v_mfma_f32_16x16x32_bf16 v[10:13], v[180:183], v[230:233], v[10:13]
	v_mfma_f32_16x16x32_bf16 v[54:57], v[184:187], v[202:205], v[54:57]
	v_mfma_f32_16x16x32_bf16 v[50:53], v[192:195], v[202:205], v[50:53]
	v_mfma_f32_16x16x32_bf16 v[38:41], v[184:187], v[210:213], v[38:41]
	v_mfma_f32_16x16x32_bf16 v[34:37], v[192:195], v[210:213], v[34:37]
	v_mfma_f32_16x16x32_bf16 v[22:25], v[184:187], v[218:221], v[22:25]
	v_mfma_f32_16x16x32_bf16 v[18:21], v[192:195], v[218:221], v[18:21]
	v_mfma_f32_16x16x32_bf16 v[6:9], v[184:187], v[226:229], v[6:9]
	v_mfma_f32_16x16x32_bf16 v[2:5], v[192:195], v[226:229], v[2:5]
	v_mfma_f32_16x16x32_bf16 v[54:57], v[188:191], v[206:209], v[54:57]
	v_mfma_f32_16x16x32_bf16 v[50:53], v[198:201], v[206:209], v[50:53]
	v_mfma_f32_16x16x32_bf16 v[38:41], v[188:191], v[214:217], v[38:41]
	v_mfma_f32_16x16x32_bf16 v[34:37], v[198:201], v[214:217], v[34:37]
	v_mfma_f32_16x16x32_bf16 v[22:25], v[188:191], v[222:225], v[22:25]
	v_mfma_f32_16x16x32_bf16 v[18:21], v[198:201], v[222:225], v[18:21]
	v_mfma_f32_16x16x32_bf16 v[6:9], v[188:191], v[230:233], v[6:9]
	v_mfma_f32_16x16x32_bf16 v[2:5], v[198:201], v[230:233], v[2:5]
	s_barrier
	s_setprio 0
	s_add_i32 s29, s29, 2
	s_add_u32 s8, s8, 0x100
	s_addc_u32 s9, s9, 0
	s_add_u32 s21, s21, 0x100
	s_addc_u32 s28, s28, 0
	s_cmp_gt_u32 s29, 61
	.p2align	8

.LBB0_677:
	s_ashr_i32 s47, s46, 31
	s_lshl_b64 s[48:49], s[46:47], 21
	s_add_u32 s48, s86, s48
	s_addc_u32 s49, s87, s49
	s_and_b64 s[50:51], s[4:5], exec
	s_cselect_b32 s7, s49, s59
	s_cselect_b32 s47, s48, s58
	s_ashr_i32 s45, s44, 31
	s_lshl_b64 s[50:51], s[44:45], 21
	s_add_u32 s50, s82, s50
	s_addc_u32 s51, s83, s51
	s_and_b64 s[62:63], s[4:5], exec
	s_cselect_b32 s45, s51, s61
	s_cselect_b32 s57, s50, s60
	s_add_u32 s58, s58, 0x100080
	s_addc_u32 s59, s59, 0
	s_add_u32 s76, s60, 0x100
	s_addc_u32 s77, s61, 0
	s_mov_b32 s78, -2
	s_waitcnt lgkmcnt(0)
	ds_read_b128 v[148:151], v159
	ds_read_b128 v[152:155], v159 offset:1024
	ds_read_b128 v[164:167], v159 offset:2048
	ds_read_b128 v[168:171], v159 offset:3072
	ds_read_b128 v[172:175], v160
	ds_read_b128 v[176:179], v160 offset:1024
	ds_read_b128 v[180:183], v160 offset:2048
	ds_read_b128 v[184:187], v160 offset:3072
	s_add_u32 s60, s58, 0xfff00080
	s_addc_u32 s61, s59, -1
	s_cmp_eq_u32 s78, 60
	s_cselect_b32 s63, s7, s61
	s_cselect_b32 s62, s47, s60
	s_cselect_b32 s61, s45, s77
	s_cselect_b32 s60, s57, s76
	s_add_i32 m0, s64, 0xc000
	ds_read_b128 v[188:191], v161
	ds_read_b128 v[192:195], v161 offset:1024
	ds_read_b128 v[198:201], v161 offset:2048
	ds_read_b128 v[202:205], v161 offset:3072
	ds_read_b128 v[206:209], v161 offset:4096
	ds_read_b128 v[210:213], v161 offset:5120
	ds_read_b128 v[214:217], v161 offset:6144
	ds_read_b128 v[218:221], v161 offset:7168
	global_load_lds_dwordx4 v140, s[58:59]
	s_add_i32 m0, s64, 0xe000
	s_nop 0
	global_load_lds_dwordx4 v142, s[58:59]
	s_waitcnt vmcnt(8)
	s_waitcnt lgkmcnt(0)
	s_setprio 1
	s_barrier
	v_mfma_f32_16x16x32_bf16 v[126:129], v[148:151], v[188:191], 0
	v_mfma_f32_16x16x32_bf16 v[122:125], v[164:167], v[188:191], 0
	v_mfma_f32_16x16x32_bf16 v[110:113], v[148:151], v[198:201], 0
	v_mfma_f32_16x16x32_bf16 v[106:109], v[164:167], v[198:201], 0
	v_mfma_f32_16x16x32_bf16 v[94:97], v[148:151], v[206:209], 0
	v_mfma_f32_16x16x32_bf16 v[90:93], v[164:167], v[206:209], 0
	v_mfma_f32_16x16x32_bf16 v[78:81], v[148:151], v[214:217], 0
	v_mfma_f32_16x16x32_bf16 v[74:77], v[164:167], v[214:217], 0
	v_mfma_f32_16x16x32_bf16 v[126:129], v[152:155], v[192:195], v[126:129]
	v_mfma_f32_16x16x32_bf16 v[122:125], v[168:171], v[192:195], v[122:125]
	v_mfma_f32_16x16x32_bf16 v[110:113], v[152:155], v[202:205], v[110:113]
	v_mfma_f32_16x16x32_bf16 v[106:109], v[168:171], v[202:205], v[106:109]
	v_mfma_f32_16x16x32_bf16 v[94:97], v[152:155], v[210:213], v[94:97]
	v_mfma_f32_16x16x32_bf16 v[90:93], v[168:171], v[210:213], v[90:93]
	v_mfma_f32_16x16x32_bf16 v[78:81], v[152:155], v[218:221], v[78:81]
	v_mfma_f32_16x16x32_bf16 v[74:77], v[168:171], v[218:221], v[74:77]
	v_mfma_f32_16x16x32_bf16 v[118:121], v[172:175], v[188:191], 0
	v_mfma_f32_16x16x32_bf16 v[114:117], v[180:183], v[188:191], 0
	v_mfma_f32_16x16x32_bf16 v[102:105], v[172:175], v[198:201], 0
	v_mfma_f32_16x16x32_bf16 v[98:101], v[180:183], v[198:201], 0
	v_mfma_f32_16x16x32_bf16 v[86:89], v[172:175], v[206:209], 0
	v_mfma_f32_16x16x32_bf16 v[82:85], v[180:183], v[206:209], 0
	v_mfma_f32_16x16x32_bf16 v[70:73], v[172:175], v[214:217], 0
	v_mfma_f32_16x16x32_bf16 v[66:69], v[180:183], v[214:217], 0
	v_mfma_f32_16x16x32_bf16 v[118:121], v[176:179], v[192:195], v[118:121]
	v_mfma_f32_16x16x32_bf16 v[114:117], v[184:187], v[192:195], v[114:117]
	v_mfma_f32_16x16x32_bf16 v[102:105], v[176:179], v[202:205], v[102:105]
	v_mfma_f32_16x16x32_bf16 v[98:101], v[184:187], v[202:205], v[98:101]
	v_mfma_f32_16x16x32_bf16 v[86:89], v[176:179], v[210:213], v[86:89]
	v_mfma_f32_16x16x32_bf16 v[82:85], v[184:187], v[210:213], v[82:85]
	v_mfma_f32_16x16x32_bf16 v[70:73], v[176:179], v[218:221], v[70:73]
	v_mfma_f32_16x16x32_bf16 v[66:69], v[184:187], v[218:221], v[66:69]
	s_barrier
	s_setprio 0
	s_add_i32 s79, s74, s33
	s_mov_b32 m0, s79
	ds_read_b128 v[188:191], v161 offset:16384
	ds_read_b128 v[192:195], v161 offset:17408
	ds_read_b128 v[198:201], v161 offset:18432
	ds_read_b128 v[202:205], v161 offset:19456
	ds_read_b128 v[206:209], v161 offset:20480
	ds_read_b128 v[210:213], v161 offset:21504
	ds_read_b128 v[214:217], v161 offset:22528
	ds_read_b128 v[218:221], v161 offset:23552
	global_load_lds_dwordx4 v132, s[60:61]
	s_add_i32 m0, s79, 0x2000
	s_add_u32 s80, s60, 0x100000
	s_addc_u32 s81, s61, 0
	s_add_i32 s79, s75, s33
	global_load_lds_dwordx4 v136, s[60:61]
	s_mov_b32 m0, s79
	global_load_lds_dwordx4 v132, s[80:81]
	s_add_i32 m0, s79, 0x2000
	s_nop 0
	global_load_lds_dwordx4 v136, s[80:81]
	s_mov_b32 m0, s64
	s_nop 0
	global_load_lds_dwordx4 v130, s[62:63]
	s_mov_b32 m0, s65
	s_nop 0
	global_load_lds_dwordx4 v134, s[62:63]
	s_waitcnt vmcnt(8)
	s_waitcnt lgkmcnt(0)
	s_setprio 1
	s_barrier
	v_mfma_f32_16x16x32_bf16 v[62:65], v[148:151], v[188:191], 0
	v_mfma_f32_16x16x32_bf16 v[58:61], v[164:167], v[188:191], 0
	v_mfma_f32_16x16x32_bf16 v[46:49], v[148:151], v[198:201], 0
	v_mfma_f32_16x16x32_bf16 v[42:45], v[164:167], v[198:201], 0
	v_mfma_f32_16x16x32_bf16 v[30:33], v[148:151], v[206:209], 0
	v_mfma_f32_16x16x32_bf16 v[26:29], v[164:167], v[206:209], 0
	v_mfma_f32_16x16x32_bf16 v[14:17], v[148:151], v[214:217], 0
	v_mfma_f32_16x16x32_bf16 v[10:13], v[164:167], v[214:217], 0
	v_mfma_f32_16x16x32_bf16 v[62:65], v[152:155], v[192:195], v[62:65]
	v_mfma_f32_16x16x32_bf16 v[58:61], v[168:171], v[192:195], v[58:61]
	v_mfma_f32_16x16x32_bf16 v[46:49], v[152:155], v[202:205], v[46:49]
	v_mfma_f32_16x16x32_bf16 v[42:45], v[168:171], v[202:205], v[42:45]
	v_mfma_f32_16x16x32_bf16 v[30:33], v[152:155], v[210:213], v[30:33]
	v_mfma_f32_16x16x32_bf16 v[26:29], v[168:171], v[210:213], v[26:29]
	v_mfma_f32_16x16x32_bf16 v[14:17], v[152:155], v[218:221], v[14:17]
	v_mfma_f32_16x16x32_bf16 v[10:13], v[168:171], v[218:221], v[10:13]
	v_mfma_f32_16x16x32_bf16 v[54:57], v[172:175], v[188:191], 0
	v_mfma_f32_16x16x32_bf16 v[50:53], v[180:183], v[188:191], 0
	v_mfma_f32_16x16x32_bf16 v[38:41], v[172:175], v[198:201], 0
	v_mfma_f32_16x16x32_bf16 v[34:37], v[180:183], v[198:201], 0
	v_mfma_f32_16x16x32_bf16 v[22:25], v[172:175], v[206:209], 0
	v_mfma_f32_16x16x32_bf16 v[18:21], v[180:183], v[206:209], 0
	v_mfma_f32_16x16x32_bf16 v[6:9], v[172:175], v[214:217], 0
	v_mfma_f32_16x16x32_bf16 v[2:5], v[180:183], v[214:217], 0
	v_mfma_f32_16x16x32_bf16 v[54:57], v[176:179], v[192:195], v[54:57]
	v_mfma_f32_16x16x32_bf16 v[50:53], v[184:187], v[192:195], v[50:53]
	v_mfma_f32_16x16x32_bf16 v[38:41], v[176:179], v[202:205], v[38:41]
	v_mfma_f32_16x16x32_bf16 v[34:37], v[184:187], v[202:205], v[34:37]
	v_mfma_f32_16x16x32_bf16 v[22:25], v[176:179], v[210:213], v[22:25]
	v_mfma_f32_16x16x32_bf16 v[18:21], v[184:187], v[210:213], v[18:21]
	v_mfma_f32_16x16x32_bf16 v[6:9], v[176:179], v[218:221], v[6:9]
	v_mfma_f32_16x16x32_bf16 v[2:5], v[184:187], v[218:221], v[2:5]
	s_barrier
	s_setprio 0
	s_add_i32 s79, 0, 0x18000
	v_add_u32_e32 v138, s79, v157
	s_add_i32 s80, 0, 0x1c000
	ds_read_b128 v[148:151], v138
	ds_read_b128 v[152:155], v138 offset:1024
	ds_read_b128 v[164:167], v138 offset:2048
	ds_read_b128 v[168:171], v138 offset:3072
	v_add_u32_e32 v138, s80, v157
	ds_read_b128 v[172:175], v138
	ds_read_b128 v[176:179], v138 offset:1024
	ds_read_b128 v[180:183], v138 offset:2048
	ds_read_b128 v[184:187], v138 offset:3072
	s_add_u32 s62, s62, 0x100000
	s_addc_u32 s63, s63, 0
	s_mov_b32 m0, s66
	ds_read_b128 v[188:191], v161 offset:32768
	ds_read_b128 v[192:195], v161 offset:33792
	ds_read_b128 v[198:201], v161 offset:34816
	ds_read_b128 v[202:205], v161 offset:35840
	ds_read_b128 v[206:209], v161 offset:36864
	ds_read_b128 v[210:213], v161 offset:37888
	ds_read_b128 v[214:217], v161 offset:38912
	ds_read_b128 v[218:221], v161 offset:39936
	global_load_lds_dwordx4 v130, s[62:63]
	s_mov_b32 m0, s67
	s_nop 0
	global_load_lds_dwordx4 v134, s[62:63]
	s_waitcnt vmcnt(8)
	s_waitcnt lgkmcnt(0)
	s_setprio 1
	s_barrier
	v_mfma_f32_16x16x32_bf16 v[126:129], v[148:151], v[188:191], v[126:129]
	v_mfma_f32_16x16x32_bf16 v[122:125], v[164:167], v[188:191], v[122:125]
	v_mfma_f32_16x16x32_bf16 v[110:113], v[148:151], v[198:201], v[110:113]
	v_mfma_f32_16x16x32_bf16 v[106:109], v[164:167], v[198:201], v[106:109]
	v_mfma_f32_16x16x32_bf16 v[94:97], v[148:151], v[206:209], v[94:97]
	v_mfma_f32_16x16x32_bf16 v[90:93], v[164:167], v[206:209], v[90:93]
	v_mfma_f32_16x16x32_bf16 v[78:81], v[148:151], v[214:217], v[78:81]
	v_mfma_f32_16x16x32_bf16 v[74:77], v[164:167], v[214:217], v[74:77]
	v_mfma_f32_16x16x32_bf16 v[126:129], v[152:155], v[192:195], v[126:129]
	v_mfma_f32_16x16x32_bf16 v[122:125], v[168:171], v[192:195], v[122:125]
	v_mfma_f32_16x16x32_bf16 v[110:113], v[152:155], v[202:205], v[110:113]
	v_mfma_f32_16x16x32_bf16 v[106:109], v[168:171], v[202:205], v[106:109]
	v_mfma_f32_16x16x32_bf16 v[94:97], v[152:155], v[210:213], v[94:97]
	v_mfma_f32_16x16x32_bf16 v[90:93], v[168:171], v[210:213], v[90:93]
	v_mfma_f32_16x16x32_bf16 v[78:81], v[152:155], v[218:221], v[78:81]
	v_mfma_f32_16x16x32_bf16 v[74:77], v[168:171], v[218:221], v[74:77]
	v_mfma_f32_16x16x32_bf16 v[118:121], v[172:175], v[188:191], v[118:121]
	v_mfma_f32_16x16x32_bf16 v[114:117], v[180:183], v[188:191], v[114:117]
	v_mfma_f32_16x16x32_bf16 v[102:105], v[172:175], v[198:201], v[102:105]
	v_mfma_f32_16x16x32_bf16 v[98:101], v[180:183], v[198:201], v[98:101]
	v_mfma_f32_16x16x32_bf16 v[86:89], v[172:175], v[206:209], v[86:89]
	v_mfma_f32_16x16x32_bf16 v[82:85], v[180:183], v[206:209], v[82:85]
	v_mfma_f32_16x16x32_bf16 v[70:73], v[172:175], v[214:217], v[70:73]
	v_mfma_f32_16x16x32_bf16 v[66:69], v[180:183], v[214:217], v[66:69]
	v_mfma_f32_16x16x32_bf16 v[118:121], v[176:179], v[192:195], v[118:121]
	v_mfma_f32_16x16x32_bf16 v[114:117], v[184:187], v[192:195], v[114:117]
	v_mfma_f32_16x16x32_bf16 v[102:105], v[176:179], v[202:205], v[102:105]
	v_mfma_f32_16x16x32_bf16 v[98:101], v[184:187], v[202:205], v[98:101]
	v_mfma_f32_16x16x32_bf16 v[86:89], v[176:179], v[210:213], v[86:89]
	v_mfma_f32_16x16x32_bf16 v[82:85], v[184:187], v[210:213], v[82:85]
	v_mfma_f32_16x16x32_bf16 v[70:73], v[176:179], v[218:221], v[70:73]
	v_mfma_f32_16x16x32_bf16 v[66:69], v[184:187], v[218:221], v[66:69]
	s_barrier
	s_setprio 0
	s_add_u32 s60, s60, 0x80
	s_addc_u32 s61, s61, 0
	s_add_i32 m0, s33, 0x18000
	ds_read_b128 v[188:191], v161 offset:49152
	ds_read_b128 v[192:195], v161 offset:50176
	ds_read_b128 v[198:201], v161 offset:51200
	ds_read_b128 v[202:205], v161 offset:52224
	ds_read_b128 v[206:209], v161 offset:53248
	ds_read_b128 v[210:213], v161 offset:54272
	ds_read_b128 v[214:217], v161 offset:55296
	ds_read_b128 v[218:221], v161 offset:56320
	global_load_lds_dwordx4 v132, s[60:61]
	s_add_i32 m0, s33, 0x1a000
	s_add_u32 s62, s62, 0xfff00080
	global_load_lds_dwordx4 v136, s[60:61]
	s_addc_u32 s63, s63, -1
	s_add_u32 s60, s60, 0x100000
	s_addc_u32 s61, s61, 0
	s_add_i32 m0, s33, 0x1c000
	s_nop 0
	global_load_lds_dwordx4 v132, s[60:61]
	s_add_i32 m0, s33, 0x1e000
	s_nop 0
	global_load_lds_dwordx4 v136, s[60:61]
	s_mov_b32 m0, s69
	s_nop 0
	global_load_lds_dwordx4 v130, s[62:63]
	s_mov_b32 m0, s70
	s_nop 0
	global_load_lds_dwordx4 v134, s[62:63]
	s_waitcnt vmcnt(8)
	s_waitcnt lgkmcnt(0)
	s_setprio 1
	s_barrier
	v_mfma_f32_16x16x32_bf16 v[62:65], v[148:151], v[188:191], v[62:65]
	v_mfma_f32_16x16x32_bf16 v[58:61], v[164:167], v[188:191], v[58:61]
	v_mfma_f32_16x16x32_bf16 v[46:49], v[148:151], v[198:201], v[46:49]
	v_mfma_f32_16x16x32_bf16 v[42:45], v[164:167], v[198:201], v[42:45]
	v_mfma_f32_16x16x32_bf16 v[30:33], v[148:151], v[206:209], v[30:33]
	v_mfma_f32_16x16x32_bf16 v[26:29], v[164:167], v[206:209], v[26:29]
	v_mfma_f32_16x16x32_bf16 v[14:17], v[148:151], v[214:217], v[14:17]
	v_mfma_f32_16x16x32_bf16 v[10:13], v[164:167], v[214:217], v[10:13]
	v_mfma_f32_16x16x32_bf16 v[62:65], v[152:155], v[192:195], v[62:65]
	v_mfma_f32_16x16x32_bf16 v[58:61], v[168:171], v[192:195], v[58:61]
	v_mfma_f32_16x16x32_bf16 v[46:49], v[152:155], v[202:205], v[46:49]
	v_mfma_f32_16x16x32_bf16 v[42:45], v[168:171], v[202:205], v[42:45]
	v_mfma_f32_16x16x32_bf16 v[30:33], v[152:155], v[210:213], v[30:33]
	v_mfma_f32_16x16x32_bf16 v[26:29], v[168:171], v[210:213], v[26:29]
	v_mfma_f32_16x16x32_bf16 v[14:17], v[152:155], v[218:221], v[14:17]
	v_mfma_f32_16x16x32_bf16 v[10:13], v[168:171], v[218:221], v[10:13]
	v_mfma_f32_16x16x32_bf16 v[54:57], v[172:175], v[188:191], v[54:57]
	v_mfma_f32_16x16x32_bf16 v[50:53], v[180:183], v[188:191], v[50:53]
	v_mfma_f32_16x16x32_bf16 v[38:41], v[172:175], v[198:201], v[38:41]
	v_mfma_f32_16x16x32_bf16 v[34:37], v[180:183], v[198:201], v[34:37]
	v_mfma_f32_16x16x32_bf16 v[22:25], v[172:175], v[206:209], v[22:25]
	v_mfma_f32_16x16x32_bf16 v[18:21], v[180:183], v[206:209], v[18:21]
	v_mfma_f32_16x16x32_bf16 v[6:9], v[172:175], v[214:217], v[6:9]
	v_mfma_f32_16x16x32_bf16 v[2:5], v[180:183], v[214:217], v[2:5]
	v_mfma_f32_16x16x32_bf16 v[54:57], v[176:179], v[192:195], v[54:57]
	v_mfma_f32_16x16x32_bf16 v[50:53], v[184:187], v[192:195], v[50:53]
	v_mfma_f32_16x16x32_bf16 v[38:41], v[176:179], v[202:205], v[38:41]
	v_mfma_f32_16x16x32_bf16 v[34:37], v[184:187], v[202:205], v[34:37]
	v_mfma_f32_16x16x32_bf16 v[22:25], v[176:179], v[210:213], v[22:25]
	v_mfma_f32_16x16x32_bf16 v[18:21], v[184:187], v[210:213], v[18:21]
	v_mfma_f32_16x16x32_bf16 v[6:9], v[176:179], v[218:221], v[6:9]
	v_mfma_f32_16x16x32_bf16 v[2:5], v[184:187], v[218:221], v[2:5]
	s_barrier
	s_setprio 0
	s_add_i32 s78, s78, 2
	s_add_u32 s58, s58, 0x100
	s_addc_u32 s59, s59, 0
	s_add_u32 s76, s76, 0x100
	s_addc_u32 s77, s77, 0
	s_cmp_gt_u32 s78, 61
	.p2align	8

.LBB0_806:
	s_ashr_i32 s35, s34, 31
	s_lshl_b64 s[36:37], s[34:35], 21
	s_add_u32 s36, s8, s36
	s_addc_u32 s37, s9, s37
	s_and_b64 s[38:39], s[0:1], exec
	s_cselect_b32 s35, s37, s43
	s_cselect_b32 s64, s36, s42
	s_ashr_i32 s31, s30, 31
	s_lshl_b64 s[38:39], s[30:31], 21
	s_add_u32 s38, s76, s38
	s_addc_u32 s39, s77, s39
	s_and_b64 s[46:47], s[0:1], exec
	s_cselect_b32 s31, s39, s45
	s_cselect_b32 s65, s38, s44
	s_add_u32 s42, s42, 0x100080
	s_addc_u32 s43, s43, 0
	s_add_u32 s66, s44, 0x100
	s_addc_u32 s67, s45, 0
	s_mov_b32 s68, -2
	ds_read_b128 v[154:157], v150
	ds_read_b128 v[158:161], v150 offset:1024
	ds_read_b128 v[162:165], v150 offset:2048
	ds_read_b128 v[166:169], v150 offset:3072
	ds_read_b128 v[170:173], v151
	ds_read_b128 v[174:177], v151 offset:1024
	ds_read_b128 v[178:181], v151 offset:2048
	ds_read_b128 v[182:185], v151 offset:3072
	s_add_u32 s44, s42, 0xfff00080
	s_addc_u32 s45, s43, -1
	s_cmp_eq_u32 s68, 60
	s_cselect_b32 s47, s35, s45
	s_cselect_b32 s46, s64, s44
	s_cselect_b32 s45, s31, s67
	s_cselect_b32 s44, s65, s66
	s_add_i32 m0, s41, 0xc000
	ds_read_b128 v[186:189], v152
	ds_read_b128 v[190:193], v152 offset:1024
	ds_read_b128 v[198:201], v152 offset:2048
	ds_read_b128 v[202:205], v152 offset:3072
	ds_read_b128 v[206:209], v152 offset:4096
	ds_read_b128 v[210:213], v152 offset:5120
	ds_read_b128 v[214:217], v152 offset:6144
	ds_read_b128 v[218:221], v152 offset:7168
	global_load_lds_dwordx4 v138, s[42:43]
	s_add_i32 m0, s41, 0xe000
	s_nop 0
	global_load_lds_dwordx4 v140, s[42:43]
	s_waitcnt vmcnt(8)
	s_waitcnt lgkmcnt(0)
	s_setprio 1
	s_barrier
	v_mfma_f32_16x16x32_bf16 v[126:129], v[154:157], v[186:189], 0
	v_mfma_f32_16x16x32_bf16 v[122:125], v[162:165], v[186:189], 0
	v_mfma_f32_16x16x32_bf16 v[110:113], v[154:157], v[198:201], 0
	v_mfma_f32_16x16x32_bf16 v[106:109], v[162:165], v[198:201], 0
	v_mfma_f32_16x16x32_bf16 v[94:97], v[154:157], v[206:209], 0
	v_mfma_f32_16x16x32_bf16 v[90:93], v[162:165], v[206:209], 0
	v_mfma_f32_16x16x32_bf16 v[78:81], v[154:157], v[214:217], 0
	v_mfma_f32_16x16x32_bf16 v[74:77], v[162:165], v[214:217], 0
	v_mfma_f32_16x16x32_bf16 v[126:129], v[158:161], v[190:193], v[126:129]
	v_mfma_f32_16x16x32_bf16 v[122:125], v[166:169], v[190:193], v[122:125]
	v_mfma_f32_16x16x32_bf16 v[110:113], v[158:161], v[202:205], v[110:113]
	v_mfma_f32_16x16x32_bf16 v[106:109], v[166:169], v[202:205], v[106:109]
	v_mfma_f32_16x16x32_bf16 v[94:97], v[158:161], v[210:213], v[94:97]
	v_mfma_f32_16x16x32_bf16 v[90:93], v[166:169], v[210:213], v[90:93]
	v_mfma_f32_16x16x32_bf16 v[78:81], v[158:161], v[218:221], v[78:81]
	v_mfma_f32_16x16x32_bf16 v[74:77], v[166:169], v[218:221], v[74:77]
	v_mfma_f32_16x16x32_bf16 v[118:121], v[170:173], v[186:189], 0
	v_mfma_f32_16x16x32_bf16 v[114:117], v[178:181], v[186:189], 0
	v_mfma_f32_16x16x32_bf16 v[102:105], v[170:173], v[198:201], 0
	v_mfma_f32_16x16x32_bf16 v[98:101], v[178:181], v[198:201], 0
	v_mfma_f32_16x16x32_bf16 v[86:89], v[170:173], v[206:209], 0
	v_mfma_f32_16x16x32_bf16 v[82:85], v[178:181], v[206:209], 0
	v_mfma_f32_16x16x32_bf16 v[70:73], v[170:173], v[214:217], 0
	v_mfma_f32_16x16x32_bf16 v[66:69], v[178:181], v[214:217], 0
	v_mfma_f32_16x16x32_bf16 v[118:121], v[174:177], v[190:193], v[118:121]
	v_mfma_f32_16x16x32_bf16 v[114:117], v[182:185], v[190:193], v[114:117]
	v_mfma_f32_16x16x32_bf16 v[102:105], v[174:177], v[202:205], v[102:105]
	v_mfma_f32_16x16x32_bf16 v[98:101], v[182:185], v[202:205], v[98:101]
	v_mfma_f32_16x16x32_bf16 v[86:89], v[174:177], v[210:213], v[86:89]
	v_mfma_f32_16x16x32_bf16 v[82:85], v[182:185], v[210:213], v[82:85]
	v_mfma_f32_16x16x32_bf16 v[70:73], v[174:177], v[218:221], v[70:73]
	v_mfma_f32_16x16x32_bf16 v[66:69], v[182:185], v[218:221], v[66:69]
	s_barrier
	s_setprio 0
	s_add_i32 s69, s57, s33
	s_mov_b32 m0, s69
	ds_read_b128 v[186:189], v152 offset:16384
	ds_read_b128 v[190:193], v152 offset:17408
	ds_read_b128 v[198:201], v152 offset:18432
	ds_read_b128 v[202:205], v152 offset:19456
	ds_read_b128 v[206:209], v152 offset:20480
	ds_read_b128 v[210:213], v152 offset:21504
	ds_read_b128 v[214:217], v152 offset:22528
	ds_read_b128 v[218:221], v152 offset:23552
	global_load_lds_dwordx4 v132, s[44:45]
	s_add_i32 m0, s69, 0x2000
	s_add_u32 s70, s44, 0x100000
	s_addc_u32 s71, s45, 0
	s_add_i32 s69, s58, s33
	global_load_lds_dwordx4 v136, s[44:45]
	s_mov_b32 m0, s69
	global_load_lds_dwordx4 v132, s[70:71]
	s_add_i32 m0, s69, 0x2000
	s_nop 0
	global_load_lds_dwordx4 v136, s[70:71]
	s_mov_b32 m0, s41
	s_nop 0
	global_load_lds_dwordx4 v130, s[46:47]
	s_mov_b32 m0, s50
	s_nop 0
	global_load_lds_dwordx4 v134, s[46:47]
	s_waitcnt vmcnt(8)
	s_waitcnt lgkmcnt(0)
	s_setprio 1
	s_barrier
	v_mfma_f32_16x16x32_bf16 v[62:65], v[154:157], v[186:189], 0
	v_mfma_f32_16x16x32_bf16 v[58:61], v[162:165], v[186:189], 0
	v_mfma_f32_16x16x32_bf16 v[46:49], v[154:157], v[198:201], 0
	v_mfma_f32_16x16x32_bf16 v[42:45], v[162:165], v[198:201], 0
	v_mfma_f32_16x16x32_bf16 v[30:33], v[154:157], v[206:209], 0
	v_mfma_f32_16x16x32_bf16 v[26:29], v[162:165], v[206:209], 0
	v_mfma_f32_16x16x32_bf16 v[14:17], v[154:157], v[214:217], 0
	v_mfma_f32_16x16x32_bf16 v[10:13], v[162:165], v[214:217], 0
	v_mfma_f32_16x16x32_bf16 v[62:65], v[158:161], v[190:193], v[62:65]
	v_mfma_f32_16x16x32_bf16 v[58:61], v[166:169], v[190:193], v[58:61]
	v_mfma_f32_16x16x32_bf16 v[46:49], v[158:161], v[202:205], v[46:49]
	v_mfma_f32_16x16x32_bf16 v[42:45], v[166:169], v[202:205], v[42:45]
	v_mfma_f32_16x16x32_bf16 v[30:33], v[158:161], v[210:213], v[30:33]
	v_mfma_f32_16x16x32_bf16 v[26:29], v[166:169], v[210:213], v[26:29]
	v_mfma_f32_16x16x32_bf16 v[14:17], v[158:161], v[218:221], v[14:17]
	v_mfma_f32_16x16x32_bf16 v[10:13], v[166:169], v[218:221], v[10:13]
	v_mfma_f32_16x16x32_bf16 v[54:57], v[170:173], v[186:189], 0
	v_mfma_f32_16x16x32_bf16 v[50:53], v[178:181], v[186:189], 0
	v_mfma_f32_16x16x32_bf16 v[38:41], v[170:173], v[198:201], 0
	v_mfma_f32_16x16x32_bf16 v[34:37], v[178:181], v[198:201], 0
	v_mfma_f32_16x16x32_bf16 v[22:25], v[170:173], v[206:209], 0
	v_mfma_f32_16x16x32_bf16 v[18:21], v[178:181], v[206:209], 0
	v_mfma_f32_16x16x32_bf16 v[6:9], v[170:173], v[214:217], 0
	v_mfma_f32_16x16x32_bf16 v[2:5], v[178:181], v[214:217], 0
	v_mfma_f32_16x16x32_bf16 v[54:57], v[174:177], v[190:193], v[54:57]
	v_mfma_f32_16x16x32_bf16 v[50:53], v[182:185], v[190:193], v[50:53]
	v_mfma_f32_16x16x32_bf16 v[38:41], v[174:177], v[202:205], v[38:41]
	v_mfma_f32_16x16x32_bf16 v[34:37], v[182:185], v[202:205], v[34:37]
	v_mfma_f32_16x16x32_bf16 v[22:25], v[174:177], v[210:213], v[22:25]
	v_mfma_f32_16x16x32_bf16 v[18:21], v[182:185], v[210:213], v[18:21]
	v_mfma_f32_16x16x32_bf16 v[6:9], v[174:177], v[218:221], v[6:9]
	v_mfma_f32_16x16x32_bf16 v[2:5], v[182:185], v[218:221], v[2:5]
	s_barrier
	s_setprio 0
	s_add_i32 s69, 0, 0x18000
	v_add_u32_e32 v153, s69, v148
	s_add_i32 s70, 0, 0x1c000
	ds_read_b128 v[154:157], v153
	ds_read_b128 v[158:161], v153 offset:1024
	ds_read_b128 v[162:165], v153 offset:2048
	ds_read_b128 v[166:169], v153 offset:3072
	v_add_u32_e32 v153, s70, v148
	ds_read_b128 v[170:173], v153
	ds_read_b128 v[174:177], v153 offset:1024
	ds_read_b128 v[178:181], v153 offset:2048
	ds_read_b128 v[182:185], v153 offset:3072
	s_add_u32 s46, s46, 0x100000
	s_addc_u32 s47, s47, 0
	s_mov_b32 m0, s51
	ds_read_b128 v[186:189], v152 offset:32768
	ds_read_b128 v[190:193], v152 offset:33792
	ds_read_b128 v[198:201], v152 offset:34816
	ds_read_b128 v[202:205], v152 offset:35840
	ds_read_b128 v[206:209], v152 offset:36864
	ds_read_b128 v[210:213], v152 offset:37888
	ds_read_b128 v[214:217], v152 offset:38912
	ds_read_b128 v[218:221], v152 offset:39936
	global_load_lds_dwordx4 v130, s[46:47]
	s_mov_b32 m0, s52
	s_nop 0
	global_load_lds_dwordx4 v134, s[46:47]
	s_waitcnt vmcnt(8)
	s_waitcnt lgkmcnt(0)
	s_setprio 1
	s_barrier
	v_mfma_f32_16x16x32_bf16 v[126:129], v[154:157], v[186:189], v[126:129]
	v_mfma_f32_16x16x32_bf16 v[122:125], v[162:165], v[186:189], v[122:125]
	v_mfma_f32_16x16x32_bf16 v[110:113], v[154:157], v[198:201], v[110:113]
	v_mfma_f32_16x16x32_bf16 v[106:109], v[162:165], v[198:201], v[106:109]
	v_mfma_f32_16x16x32_bf16 v[94:97], v[154:157], v[206:209], v[94:97]
	v_mfma_f32_16x16x32_bf16 v[90:93], v[162:165], v[206:209], v[90:93]
	v_mfma_f32_16x16x32_bf16 v[78:81], v[154:157], v[214:217], v[78:81]
	v_mfma_f32_16x16x32_bf16 v[74:77], v[162:165], v[214:217], v[74:77]
	v_mfma_f32_16x16x32_bf16 v[126:129], v[158:161], v[190:193], v[126:129]
	v_mfma_f32_16x16x32_bf16 v[122:125], v[166:169], v[190:193], v[122:125]
	v_mfma_f32_16x16x32_bf16 v[110:113], v[158:161], v[202:205], v[110:113]
	v_mfma_f32_16x16x32_bf16 v[106:109], v[166:169], v[202:205], v[106:109]
	v_mfma_f32_16x16x32_bf16 v[94:97], v[158:161], v[210:213], v[94:97]
	v_mfma_f32_16x16x32_bf16 v[90:93], v[166:169], v[210:213], v[90:93]
	v_mfma_f32_16x16x32_bf16 v[78:81], v[158:161], v[218:221], v[78:81]
	v_mfma_f32_16x16x32_bf16 v[74:77], v[166:169], v[218:221], v[74:77]
	v_mfma_f32_16x16x32_bf16 v[118:121], v[170:173], v[186:189], v[118:121]
	v_mfma_f32_16x16x32_bf16 v[114:117], v[178:181], v[186:189], v[114:117]
	v_mfma_f32_16x16x32_bf16 v[102:105], v[170:173], v[198:201], v[102:105]
	v_mfma_f32_16x16x32_bf16 v[98:101], v[178:181], v[198:201], v[98:101]
	v_mfma_f32_16x16x32_bf16 v[86:89], v[170:173], v[206:209], v[86:89]
	v_mfma_f32_16x16x32_bf16 v[82:85], v[178:181], v[206:209], v[82:85]
	v_mfma_f32_16x16x32_bf16 v[70:73], v[170:173], v[214:217], v[70:73]
	v_mfma_f32_16x16x32_bf16 v[66:69], v[178:181], v[214:217], v[66:69]
	v_mfma_f32_16x16x32_bf16 v[118:121], v[174:177], v[190:193], v[118:121]
	v_mfma_f32_16x16x32_bf16 v[114:117], v[182:185], v[190:193], v[114:117]
	v_mfma_f32_16x16x32_bf16 v[102:105], v[174:177], v[202:205], v[102:105]
	v_mfma_f32_16x16x32_bf16 v[98:101], v[182:185], v[202:205], v[98:101]
	v_mfma_f32_16x16x32_bf16 v[86:89], v[174:177], v[210:213], v[86:89]
	v_mfma_f32_16x16x32_bf16 v[82:85], v[182:185], v[210:213], v[82:85]
	v_mfma_f32_16x16x32_bf16 v[70:73], v[174:177], v[218:221], v[70:73]
	v_mfma_f32_16x16x32_bf16 v[66:69], v[182:185], v[218:221], v[66:69]
	s_barrier
	s_setprio 0
	s_add_u32 s44, s44, 0x80
	s_addc_u32 s45, s45, 0
	s_add_i32 m0, s33, 0x18000
	ds_read_b128 v[186:189], v152 offset:49152
	ds_read_b128 v[190:193], v152 offset:50176
	ds_read_b128 v[198:201], v152 offset:51200
	ds_read_b128 v[202:205], v152 offset:52224
	ds_read_b128 v[206:209], v152 offset:53248
	ds_read_b128 v[210:213], v152 offset:54272
	ds_read_b128 v[214:217], v152 offset:55296
	ds_read_b128 v[218:221], v152 offset:56320
	global_load_lds_dwordx4 v132, s[44:45]
	s_add_i32 m0, s33, 0x1a000
	s_add_u32 s46, s46, 0xfff00080
	global_load_lds_dwordx4 v136, s[44:45]
	s_addc_u32 s47, s47, -1
	s_add_u32 s44, s44, 0x100000
	s_addc_u32 s45, s45, 0
	s_add_i32 m0, s33, 0x1c000
	s_nop 0
	global_load_lds_dwordx4 v132, s[44:45]
	s_add_i32 m0, s33, 0x1e000
	s_nop 0
	global_load_lds_dwordx4 v136, s[44:45]
	s_mov_b32 m0, s55
	s_nop 0
	global_load_lds_dwordx4 v130, s[46:47]
	s_mov_b32 m0, s56
	s_nop 0
	global_load_lds_dwordx4 v134, s[46:47]
	s_waitcnt vmcnt(8)
	s_waitcnt lgkmcnt(0)
	s_setprio 1
	s_barrier
	v_mfma_f32_16x16x32_bf16 v[62:65], v[154:157], v[186:189], v[62:65]
	v_mfma_f32_16x16x32_bf16 v[58:61], v[162:165], v[186:189], v[58:61]
	v_mfma_f32_16x16x32_bf16 v[46:49], v[154:157], v[198:201], v[46:49]
	v_mfma_f32_16x16x32_bf16 v[42:45], v[162:165], v[198:201], v[42:45]
	v_mfma_f32_16x16x32_bf16 v[30:33], v[154:157], v[206:209], v[30:33]
	v_mfma_f32_16x16x32_bf16 v[26:29], v[162:165], v[206:209], v[26:29]
	v_mfma_f32_16x16x32_bf16 v[14:17], v[154:157], v[214:217], v[14:17]
	v_mfma_f32_16x16x32_bf16 v[10:13], v[162:165], v[214:217], v[10:13]
	v_mfma_f32_16x16x32_bf16 v[62:65], v[158:161], v[190:193], v[62:65]
	v_mfma_f32_16x16x32_bf16 v[58:61], v[166:169], v[190:193], v[58:61]
	v_mfma_f32_16x16x32_bf16 v[46:49], v[158:161], v[202:205], v[46:49]
	v_mfma_f32_16x16x32_bf16 v[42:45], v[166:169], v[202:205], v[42:45]
	v_mfma_f32_16x16x32_bf16 v[30:33], v[158:161], v[210:213], v[30:33]
	v_mfma_f32_16x16x32_bf16 v[26:29], v[166:169], v[210:213], v[26:29]
	v_mfma_f32_16x16x32_bf16 v[14:17], v[158:161], v[218:221], v[14:17]
	v_mfma_f32_16x16x32_bf16 v[10:13], v[166:169], v[218:221], v[10:13]
	v_mfma_f32_16x16x32_bf16 v[54:57], v[170:173], v[186:189], v[54:57]
	v_mfma_f32_16x16x32_bf16 v[50:53], v[178:181], v[186:189], v[50:53]
	v_mfma_f32_16x16x32_bf16 v[38:41], v[170:173], v[198:201], v[38:41]
	v_mfma_f32_16x16x32_bf16 v[34:37], v[178:181], v[198:201], v[34:37]
	v_mfma_f32_16x16x32_bf16 v[22:25], v[170:173], v[206:209], v[22:25]
	v_mfma_f32_16x16x32_bf16 v[18:21], v[178:181], v[206:209], v[18:21]
	v_mfma_f32_16x16x32_bf16 v[6:9], v[170:173], v[214:217], v[6:9]
	v_mfma_f32_16x16x32_bf16 v[2:5], v[178:181], v[214:217], v[2:5]
	v_mfma_f32_16x16x32_bf16 v[54:57], v[174:177], v[190:193], v[54:57]
	v_mfma_f32_16x16x32_bf16 v[50:53], v[182:185], v[190:193], v[50:53]
	v_mfma_f32_16x16x32_bf16 v[38:41], v[174:177], v[202:205], v[38:41]
	v_mfma_f32_16x16x32_bf16 v[34:37], v[182:185], v[202:205], v[34:37]
	v_mfma_f32_16x16x32_bf16 v[22:25], v[174:177], v[210:213], v[22:25]
	v_mfma_f32_16x16x32_bf16 v[18:21], v[182:185], v[210:213], v[18:21]
	v_mfma_f32_16x16x32_bf16 v[6:9], v[174:177], v[218:221], v[6:9]
	v_mfma_f32_16x16x32_bf16 v[2:5], v[182:185], v[218:221], v[2:5]
	s_barrier
	s_setprio 0
	s_add_i32 s68, s68, 2
	s_add_u32 s42, s42, 0x100
	s_addc_u32 s43, s43, 0
	s_add_u32 s66, s66, 0x100
	s_addc_u32 s67, s67, 0
	s_cmp_gt_u32 s68, 61
	.p2align	8

.LBB0_896:
	s_ashr_i32 s35, s34, 31
	s_lshl_b64 s[36:37], s[34:35], 23
	s_add_u32 s36, s86, s36
	s_addc_u32 s37, s87, s37
	s_and_b64 s[38:39], s[0:1], exec
	s_cselect_b32 s35, s37, s43
	s_cselect_b32 s63, s36, s42
	s_ashr_i32 s31, s30, 31
	s_lshl_b64 s[38:39], s[30:31], 23
	s_add_u32 s38, s10, s38
	s_addc_u32 s39, s11, s39
	s_and_b64 s[46:47], s[0:1], exec
	s_cselect_b32 s31, s39, s45
	s_cselect_b32 s64, s38, s44
	s_add_u32 s42, s42, 0x400080
	s_addc_u32 s43, s43, 0
	s_add_u32 s65, s44, 0x100
	s_addc_u32 s66, s45, 0
	s_mov_b32 s67, -2
	ds_read_b128 v[146:149], v156
	ds_read_b128 v[150:153], v156 offset:1024
	ds_read_b128 v[160:163], v156 offset:2048
	ds_read_b128 v[164:167], v156 offset:3072
	ds_read_b128 v[168:171], v157
	ds_read_b128 v[172:175], v157 offset:1024
	ds_read_b128 v[176:179], v157 offset:2048
	ds_read_b128 v[180:183], v157 offset:3072
	s_add_u32 s44, s42, 0xffc00080
	s_addc_u32 s45, s43, -1
	s_cmpk_eq_i32 s67, 0xfc
	s_cselect_b32 s47, s35, s45
	s_cselect_b32 s46, s63, s44
	s_cselect_b32 s45, s31, s66
	s_cselect_b32 s44, s64, s65
	s_add_i32 m0, s41, 0xc000
	ds_read_b128 v[184:187], v158
	ds_read_b128 v[188:191], v158 offset:1024
	ds_read_b128 v[192:195], v158 offset:2048
	ds_read_b128 v[198:201], v158 offset:3072
	ds_read_b128 v[202:205], v158 offset:4096
	ds_read_b128 v[206:209], v158 offset:5120
	ds_read_b128 v[210:213], v158 offset:6144
	ds_read_b128 v[214:217], v158 offset:7168
	global_load_lds_dwordx4 v138, s[42:43]
	s_add_i32 m0, s41, 0xe000
	s_nop 0
	global_load_lds_dwordx4 v140, s[42:43]
	s_waitcnt vmcnt(8)
	s_waitcnt lgkmcnt(0)
	s_setprio 1
	s_barrier
	v_mfma_f32_16x16x32_bf16 v[126:129], v[146:149], v[184:187], 0
	v_mfma_f32_16x16x32_bf16 v[122:125], v[160:163], v[184:187], 0
	v_mfma_f32_16x16x32_bf16 v[110:113], v[146:149], v[192:195], 0
	v_mfma_f32_16x16x32_bf16 v[106:109], v[160:163], v[192:195], 0
	v_mfma_f32_16x16x32_bf16 v[94:97], v[146:149], v[202:205], 0
	v_mfma_f32_16x16x32_bf16 v[90:93], v[160:163], v[202:205], 0
	v_mfma_f32_16x16x32_bf16 v[78:81], v[146:149], v[210:213], 0
	v_mfma_f32_16x16x32_bf16 v[74:77], v[160:163], v[210:213], 0
	v_mfma_f32_16x16x32_bf16 v[126:129], v[150:153], v[188:191], v[126:129]
	v_mfma_f32_16x16x32_bf16 v[122:125], v[164:167], v[188:191], v[122:125]
	v_mfma_f32_16x16x32_bf16 v[110:113], v[150:153], v[198:201], v[110:113]
	v_mfma_f32_16x16x32_bf16 v[106:109], v[164:167], v[198:201], v[106:109]
	v_mfma_f32_16x16x32_bf16 v[94:97], v[150:153], v[206:209], v[94:97]
	v_mfma_f32_16x16x32_bf16 v[90:93], v[164:167], v[206:209], v[90:93]
	v_mfma_f32_16x16x32_bf16 v[78:81], v[150:153], v[214:217], v[78:81]
	v_mfma_f32_16x16x32_bf16 v[74:77], v[164:167], v[214:217], v[74:77]
	v_mfma_f32_16x16x32_bf16 v[118:121], v[168:171], v[184:187], 0
	v_mfma_f32_16x16x32_bf16 v[114:117], v[176:179], v[184:187], 0
	v_mfma_f32_16x16x32_bf16 v[102:105], v[168:171], v[192:195], 0
	v_mfma_f32_16x16x32_bf16 v[98:101], v[176:179], v[192:195], 0
	v_mfma_f32_16x16x32_bf16 v[86:89], v[168:171], v[202:205], 0
	v_mfma_f32_16x16x32_bf16 v[82:85], v[176:179], v[202:205], 0
	v_mfma_f32_16x16x32_bf16 v[70:73], v[168:171], v[210:213], 0
	v_mfma_f32_16x16x32_bf16 v[66:69], v[176:179], v[210:213], 0
	v_mfma_f32_16x16x32_bf16 v[118:121], v[172:175], v[188:191], v[118:121]
	v_mfma_f32_16x16x32_bf16 v[114:117], v[180:183], v[188:191], v[114:117]
	v_mfma_f32_16x16x32_bf16 v[102:105], v[172:175], v[198:201], v[102:105]
	v_mfma_f32_16x16x32_bf16 v[98:101], v[180:183], v[198:201], v[98:101]
	v_mfma_f32_16x16x32_bf16 v[86:89], v[172:175], v[206:209], v[86:89]
	v_mfma_f32_16x16x32_bf16 v[82:85], v[180:183], v[206:209], v[82:85]
	v_mfma_f32_16x16x32_bf16 v[70:73], v[172:175], v[214:217], v[70:73]
	v_mfma_f32_16x16x32_bf16 v[66:69], v[180:183], v[214:217], v[66:69]
	s_barrier
	s_setprio 0
	s_add_i32 s68, s56, s48
	s_mov_b32 m0, s68
	ds_read_b128 v[184:187], v158 offset:16384
	ds_read_b128 v[188:191], v158 offset:17408
	ds_read_b128 v[192:195], v158 offset:18432
	ds_read_b128 v[198:201], v158 offset:19456
	ds_read_b128 v[202:205], v158 offset:20480
	ds_read_b128 v[206:209], v158 offset:21504
	ds_read_b128 v[210:213], v158 offset:22528
	ds_read_b128 v[214:217], v158 offset:23552
	global_load_lds_dwordx4 v132, s[44:45]
	s_add_i32 m0, s68, 0x2000
	s_add_u32 s68, s44, 0x400000
	s_addc_u32 s69, s45, 0
	s_add_i32 s70, s57, s48
	global_load_lds_dwordx4 v136, s[44:45]
	s_mov_b32 m0, s70
	global_load_lds_dwordx4 v132, s[68:69]
	s_add_i32 m0, s70, 0x2000
	s_nop 0
	global_load_lds_dwordx4 v136, s[68:69]
	s_mov_b32 m0, s41
	s_nop 0
	global_load_lds_dwordx4 v130, s[46:47]
	s_mov_b32 m0, s49
	s_nop 0
	global_load_lds_dwordx4 v134, s[46:47]
	s_waitcnt vmcnt(8)
	s_waitcnt lgkmcnt(0)
	s_setprio 1
	s_barrier
	v_mfma_f32_16x16x32_bf16 v[62:65], v[146:149], v[184:187], 0
	v_mfma_f32_16x16x32_bf16 v[58:61], v[160:163], v[184:187], 0
	v_mfma_f32_16x16x32_bf16 v[46:49], v[146:149], v[192:195], 0
	v_mfma_f32_16x16x32_bf16 v[42:45], v[160:163], v[192:195], 0
	v_mfma_f32_16x16x32_bf16 v[30:33], v[146:149], v[202:205], 0
	v_mfma_f32_16x16x32_bf16 v[26:29], v[160:163], v[202:205], 0
	v_mfma_f32_16x16x32_bf16 v[14:17], v[146:149], v[210:213], 0
	v_mfma_f32_16x16x32_bf16 v[10:13], v[160:163], v[210:213], 0
	v_mfma_f32_16x16x32_bf16 v[62:65], v[150:153], v[188:191], v[62:65]
	v_mfma_f32_16x16x32_bf16 v[58:61], v[164:167], v[188:191], v[58:61]
	v_mfma_f32_16x16x32_bf16 v[46:49], v[150:153], v[198:201], v[46:49]
	v_mfma_f32_16x16x32_bf16 v[42:45], v[164:167], v[198:201], v[42:45]
	v_mfma_f32_16x16x32_bf16 v[30:33], v[150:153], v[206:209], v[30:33]
	v_mfma_f32_16x16x32_bf16 v[26:29], v[164:167], v[206:209], v[26:29]
	v_mfma_f32_16x16x32_bf16 v[14:17], v[150:153], v[214:217], v[14:17]
	v_mfma_f32_16x16x32_bf16 v[10:13], v[164:167], v[214:217], v[10:13]
	v_mfma_f32_16x16x32_bf16 v[54:57], v[168:171], v[184:187], 0
	v_mfma_f32_16x16x32_bf16 v[50:53], v[176:179], v[184:187], 0
	v_mfma_f32_16x16x32_bf16 v[38:41], v[168:171], v[192:195], 0
	v_mfma_f32_16x16x32_bf16 v[34:37], v[176:179], v[192:195], 0
	v_mfma_f32_16x16x32_bf16 v[22:25], v[168:171], v[202:205], 0
	v_mfma_f32_16x16x32_bf16 v[18:21], v[176:179], v[202:205], 0
	v_mfma_f32_16x16x32_bf16 v[6:9], v[168:171], v[210:213], 0
	v_mfma_f32_16x16x32_bf16 v[2:5], v[176:179], v[210:213], 0
	v_mfma_f32_16x16x32_bf16 v[54:57], v[172:175], v[188:191], v[54:57]
	v_mfma_f32_16x16x32_bf16 v[50:53], v[180:183], v[188:191], v[50:53]
	v_mfma_f32_16x16x32_bf16 v[38:41], v[172:175], v[198:201], v[38:41]
	v_mfma_f32_16x16x32_bf16 v[34:37], v[180:183], v[198:201], v[34:37]
	v_mfma_f32_16x16x32_bf16 v[22:25], v[172:175], v[206:209], v[22:25]
	v_mfma_f32_16x16x32_bf16 v[18:21], v[180:183], v[206:209], v[18:21]
	v_mfma_f32_16x16x32_bf16 v[6:9], v[172:175], v[214:217], v[6:9]
	v_mfma_f32_16x16x32_bf16 v[2:5], v[180:183], v[214:217], v[2:5]
	s_barrier
	s_setprio 0
	s_add_i32 s68, 0, 0x18000
	s_add_i32 s69, 0, 0x1c000
	v_add_u32_e32 v164, s68, v154
	v_add_u32_e32 v180, s69, v154
	ds_read_b128 v[146:149], v164
	ds_read_b128 v[150:153], v164 offset:1024
	ds_read_b128 v[160:163], v164 offset:2048
	ds_read_b128 v[164:167], v164 offset:3072
	ds_read_b128 v[168:171], v180
	ds_read_b128 v[172:175], v180 offset:1024
	ds_read_b128 v[176:179], v180 offset:2048
	ds_read_b128 v[180:183], v180 offset:3072
	s_add_u32 s46, s46, 0x400000
	s_addc_u32 s47, s47, 0
	s_mov_b32 m0, s50
	ds_read_b128 v[184:187], v158 offset:32768
	ds_read_b128 v[188:191], v158 offset:33792
	ds_read_b128 v[192:195], v158 offset:34816
	ds_read_b128 v[198:201], v158 offset:35840
	ds_read_b128 v[202:205], v158 offset:36864
	ds_read_b128 v[206:209], v158 offset:37888
	ds_read_b128 v[210:213], v158 offset:38912
	ds_read_b128 v[214:217], v158 offset:39936
	global_load_lds_dwordx4 v130, s[46:47]
	s_mov_b32 m0, s51
	s_nop 0
	global_load_lds_dwordx4 v134, s[46:47]
	s_waitcnt vmcnt(8)
	s_waitcnt lgkmcnt(0)
	s_setprio 1
	s_barrier
	v_mfma_f32_16x16x32_bf16 v[126:129], v[146:149], v[184:187], v[126:129]
	v_mfma_f32_16x16x32_bf16 v[122:125], v[160:163], v[184:187], v[122:125]
	v_mfma_f32_16x16x32_bf16 v[110:113], v[146:149], v[192:195], v[110:113]
	v_mfma_f32_16x16x32_bf16 v[106:109], v[160:163], v[192:195], v[106:109]
	v_mfma_f32_16x16x32_bf16 v[94:97], v[146:149], v[202:205], v[94:97]
	v_mfma_f32_16x16x32_bf16 v[90:93], v[160:163], v[202:205], v[90:93]
	v_mfma_f32_16x16x32_bf16 v[78:81], v[146:149], v[210:213], v[78:81]
	v_mfma_f32_16x16x32_bf16 v[74:77], v[160:163], v[210:213], v[74:77]
	v_mfma_f32_16x16x32_bf16 v[126:129], v[150:153], v[188:191], v[126:129]
	v_mfma_f32_16x16x32_bf16 v[122:125], v[164:167], v[188:191], v[122:125]
	v_mfma_f32_16x16x32_bf16 v[110:113], v[150:153], v[198:201], v[110:113]
	v_mfma_f32_16x16x32_bf16 v[106:109], v[164:167], v[198:201], v[106:109]
	v_mfma_f32_16x16x32_bf16 v[94:97], v[150:153], v[206:209], v[94:97]
	v_mfma_f32_16x16x32_bf16 v[90:93], v[164:167], v[206:209], v[90:93]
	v_mfma_f32_16x16x32_bf16 v[78:81], v[150:153], v[214:217], v[78:81]
	v_mfma_f32_16x16x32_bf16 v[74:77], v[164:167], v[214:217], v[74:77]
	v_mfma_f32_16x16x32_bf16 v[118:121], v[168:171], v[184:187], v[118:121]
	v_mfma_f32_16x16x32_bf16 v[114:117], v[176:179], v[184:187], v[114:117]
	v_mfma_f32_16x16x32_bf16 v[102:105], v[168:171], v[192:195], v[102:105]
	v_mfma_f32_16x16x32_bf16 v[98:101], v[176:179], v[192:195], v[98:101]
	v_mfma_f32_16x16x32_bf16 v[86:89], v[168:171], v[202:205], v[86:89]
	v_mfma_f32_16x16x32_bf16 v[82:85], v[176:179], v[202:205], v[82:85]
	v_mfma_f32_16x16x32_bf16 v[70:73], v[168:171], v[210:213], v[70:73]
	v_mfma_f32_16x16x32_bf16 v[66:69], v[176:179], v[210:213], v[66:69]
	v_mfma_f32_16x16x32_bf16 v[118:121], v[172:175], v[188:191], v[118:121]
	v_mfma_f32_16x16x32_bf16 v[114:117], v[180:183], v[188:191], v[114:117]
	v_mfma_f32_16x16x32_bf16 v[102:105], v[172:175], v[198:201], v[102:105]
	v_mfma_f32_16x16x32_bf16 v[98:101], v[180:183], v[198:201], v[98:101]
	v_mfma_f32_16x16x32_bf16 v[86:89], v[172:175], v[206:209], v[86:89]
	v_mfma_f32_16x16x32_bf16 v[82:85], v[180:183], v[206:209], v[82:85]
	v_mfma_f32_16x16x32_bf16 v[70:73], v[172:175], v[214:217], v[70:73]
	v_mfma_f32_16x16x32_bf16 v[66:69], v[180:183], v[214:217], v[66:69]
	s_barrier
	s_setprio 0
	s_add_u32 s44, s44, 0x80
	s_addc_u32 s45, s45, 0
	s_add_i32 m0, s48, 0x18000
	ds_read_b128 v[184:187], v158 offset:49152
	ds_read_b128 v[188:191], v158 offset:50176
	ds_read_b128 v[192:195], v158 offset:51200
	ds_read_b128 v[198:201], v158 offset:52224
	ds_read_b128 v[202:205], v158 offset:53248
	ds_read_b128 v[206:209], v158 offset:54272
	ds_read_b128 v[210:213], v158 offset:55296
	ds_read_b128 v[214:217], v158 offset:56320
	global_load_lds_dwordx4 v132, s[44:45]
	s_add_i32 m0, s48, 0x1a000
	s_add_u32 s46, s46, 0xffc00080
	global_load_lds_dwordx4 v136, s[44:45]
	s_addc_u32 s47, s47, -1
	s_add_u32 s44, s44, 0x400000
	s_addc_u32 s45, s45, 0
	s_add_i32 m0, s48, 0x1c000
	s_nop 0
	global_load_lds_dwordx4 v132, s[44:45]
	s_add_i32 m0, s48, 0x1e000
	s_nop 0
	global_load_lds_dwordx4 v136, s[44:45]
	s_mov_b32 m0, s53
	s_nop 0
	global_load_lds_dwordx4 v130, s[46:47]
	s_mov_b32 m0, s54
	s_nop 0
	global_load_lds_dwordx4 v134, s[46:47]
	s_waitcnt vmcnt(8)
	s_waitcnt lgkmcnt(0)
	s_setprio 1
	s_barrier
	v_mfma_f32_16x16x32_bf16 v[62:65], v[146:149], v[184:187], v[62:65]
	v_mfma_f32_16x16x32_bf16 v[58:61], v[160:163], v[184:187], v[58:61]
	v_mfma_f32_16x16x32_bf16 v[46:49], v[146:149], v[192:195], v[46:49]
	v_mfma_f32_16x16x32_bf16 v[42:45], v[160:163], v[192:195], v[42:45]
	v_mfma_f32_16x16x32_bf16 v[30:33], v[146:149], v[202:205], v[30:33]
	v_mfma_f32_16x16x32_bf16 v[26:29], v[160:163], v[202:205], v[26:29]
	v_mfma_f32_16x16x32_bf16 v[14:17], v[146:149], v[210:213], v[14:17]
	v_mfma_f32_16x16x32_bf16 v[10:13], v[160:163], v[210:213], v[10:13]
	v_mfma_f32_16x16x32_bf16 v[62:65], v[150:153], v[188:191], v[62:65]
	v_mfma_f32_16x16x32_bf16 v[58:61], v[164:167], v[188:191], v[58:61]
	v_mfma_f32_16x16x32_bf16 v[46:49], v[150:153], v[198:201], v[46:49]
	v_mfma_f32_16x16x32_bf16 v[42:45], v[164:167], v[198:201], v[42:45]
	v_mfma_f32_16x16x32_bf16 v[30:33], v[150:153], v[206:209], v[30:33]
	v_mfma_f32_16x16x32_bf16 v[26:29], v[164:167], v[206:209], v[26:29]
	v_mfma_f32_16x16x32_bf16 v[14:17], v[150:153], v[214:217], v[14:17]
	v_mfma_f32_16x16x32_bf16 v[10:13], v[164:167], v[214:217], v[10:13]
	v_mfma_f32_16x16x32_bf16 v[54:57], v[168:171], v[184:187], v[54:57]
	v_mfma_f32_16x16x32_bf16 v[50:53], v[176:179], v[184:187], v[50:53]
	v_mfma_f32_16x16x32_bf16 v[38:41], v[168:171], v[192:195], v[38:41]
	v_mfma_f32_16x16x32_bf16 v[34:37], v[176:179], v[192:195], v[34:37]
	v_mfma_f32_16x16x32_bf16 v[22:25], v[168:171], v[202:205], v[22:25]
	v_mfma_f32_16x16x32_bf16 v[18:21], v[176:179], v[202:205], v[18:21]
	v_mfma_f32_16x16x32_bf16 v[6:9], v[168:171], v[210:213], v[6:9]
	v_mfma_f32_16x16x32_bf16 v[2:5], v[176:179], v[210:213], v[2:5]
	v_mfma_f32_16x16x32_bf16 v[54:57], v[172:175], v[188:191], v[54:57]
	v_mfma_f32_16x16x32_bf16 v[50:53], v[180:183], v[188:191], v[50:53]
	v_mfma_f32_16x16x32_bf16 v[38:41], v[172:175], v[198:201], v[38:41]
	v_mfma_f32_16x16x32_bf16 v[34:37], v[180:183], v[198:201], v[34:37]
	v_mfma_f32_16x16x32_bf16 v[22:25], v[172:175], v[206:209], v[22:25]
	v_mfma_f32_16x16x32_bf16 v[18:21], v[180:183], v[206:209], v[18:21]
	v_mfma_f32_16x16x32_bf16 v[6:9], v[172:175], v[214:217], v[6:9]
	v_mfma_f32_16x16x32_bf16 v[2:5], v[180:183], v[214:217], v[2:5]
	s_barrier
	s_setprio 0
	s_add_i32 s67, s67, 2
	s_add_u32 s42, s42, 0x100
	s_addc_u32 s43, s43, 0
	s_add_u32 s65, s65, 0x100
	s_addc_u32 s66, s66, 0
	s_cmpk_gt_u32 s67, 0xfd
	.p2align	8
